# scan loader: counted vmcnt(28) per chunk instead of full drain every third step
# baseline (speedup 1.0000x reference)
; #define LDS_BARRIER() do { asm volatile("s_waitcnt lgkmcnt(0)" ::: "memory"); __builtin_amdgcn_s_barrier(); asm volatile("" ::: "memory"); } while (0)
; __device__ __forceinline__ void phase_scan(h16* Pdn, const h16* Tg, const h16* qkg, const float* gcg, const float* betag, const float* s2g, unsigned char* ldsb) {
;     ...
;         if (w >= 4) {
;             h16x8 R0[15], R1[15], R2[15];
;             SCAN_LD(0, R0); SCAN_ST(0, R0);
;             SCAN_LD(1, R1); SCAN_LD(2, R2); SCAN_LD(3, R0);
;             LDS_BARRIER();
; #pragma unroll 1
;             for (int n = 0; n < 63; n += 3) {
;                 SCAN_ST((n + 1) & 1, R1); if (n + 4 < 64) SCAN_LD(n + 4, R1);
;                 LDS_BARRIER();
;                 SCAN_ST((n + 2) & 1, R2); if (n + 5 < 64) SCAN_LD(n + 5, R2);
;                 LDS_BARRIER();
;                 SCAN_ST((n + 3) & 1, R0); if (n + 6 < 64) SCAN_LD(n + 6, R0);
;                 LDS_BARRIER();
.LBB0_265:
	s_andn2_b32 s7, 1, s5
	v_mov_b32_e32 v32, v204
	s_mul_i32 s7, s7, 0xf300
	s_add_i32 s7, s7, 0
	v_lshlrev_b32_e32 v205, 4, v32
	v_and_b32_e32 v196, 0xf0, v205
	v_add_u32_e32 v196, s7, v196
	v_lshrrev_b32_e32 v197, 4, v32
	s_movk_i32 s10, 0x110
	v_add_u32_e32 v206, 0x100, v32
	v_mad_u64_u32 v[198:199], s[8:9], v197, s10, v[196:197]
	v_lshrrev_b32_e32 v197, 4, v206
	s_waitcnt vmcnt(28)
	ds_write_b128 v198, v[4:7]
	ds_write_b128 v198, v[8:11] offset:17408
	v_mad_u64_u32 v[198:199], s[8:9], v197, s10, v[196:197]
	v_add_u32_e32 v197, 0x200, v32
	v_lshrrev_b32_e32 v197, 4, v197
	ds_write_b128 v198, v[12:15]
	ds_write_b128 v198, v[16:19] offset:17408
	v_mad_u64_u32 v[198:199], s[8:9], v197, s10, v[196:197]
	v_add_u32_e32 v197, 0x300, v32
	v_lshrrev_b32_e32 v197, 4, v197
	v_mad_u64_u32 v[196:197], s[8:9], v197, s10, v[196:197]
	ds_write_b128 v198, v[20:23]
	ds_write_b128 v198, v[24:27] offset:17408
	ds_write_b128 v196, v[28:31]
	ds_write_b128 v196, v[34:37] offset:17408
	v_and_b32_e32 v196, 0x70, v205
	v_add_u32_e32 v196, s7, v196
	v_ashrrev_i32_e32 v197, 3, v32
	s_movk_i32 s10, 0x90
	v_mad_u64_u32 v[198:199], s[8:9], v197, s10, v[196:197]
	v_lshl_add_u32 v197, v197, 7, v196
	ds_write_b128 v198, v[38:41] offset:34816
	ds_write_b128 v198, v[42:45] offset:44032
	ds_write_b128 v197, v[66:69] offset:53248
	v_ashrrev_i32_e32 v197, 3, v206
	v_mad_u64_u32 v[198:199], s[8:9], v197, s10, v[196:197]
	v_lshl_add_u32 v196, v197, 7, v196
	v_cmp_gt_i32_e32 vcc, 48, v32
	ds_write_b128 v198, v[70:73] offset:34816
	ds_write_b128 v198, v[90:93] offset:44032
	ds_write_b128 v196, v[94:97] offset:53248
	s_and_saveexec_b64 s[8:9], vcc
	v_lshl_add_u32 v32, v32, 4, s7
	ds_write_b128 v32, v[46:49] offset:61440
	s_or_b64 exec, exec, s[8:9]
	s_cmp_gt_u32 s5, 59
	s_cselect_b64 s[8:9], -1, 0
	s_and_b64 vcc, exec, s[8:9]
	s_cbranch_vccnz .LBB0_271
	v_mov_b32_e32 v205, v204
	s_add_i32 s10, s12, s3
	v_lshlrev_b32_e32 v38, 4, v205
	v_lshrrev_b32_e32 v4, 4, v205
	v_add_u32_e32 v70, 0x100, v205
	v_and_b32_e32 v32, 0xf0, v38
	v_add_u32_e32 v4, s10, v4
	v_lshrrev_b32_e32 v12, 4, v70
	v_add_u32_e32 v20, 0x200, v205
	v_lshl_add_u64 v[28:29], s[0:1], 0, v[32:33]
	v_lshl_add_u32 v32, v4, 12, v252
	v_add_u32_e32 v12, s10, v12
	v_lshrrev_b32_e32 v20, 4, v20
	v_add_u32_e32 v30, 0x300, v205
	v_lshl_add_u64 v[8:9], v[32:33], 1, v[28:29]
	v_lshl_add_u32 v32, v12, 12, v252
	v_add_u32_e32 v20, s10, v20
	v_lshrrev_b32_e32 v30, 4, v30
	v_lshl_add_u64 v[16:17], v[32:33], 1, v[28:29]
	v_lshl_add_u32 v32, v20, 12, v252
	v_add_u32_e32 v30, s10, v30
	v_lshl_add_u64 v[24:25], v[32:33], 1, v[28:29]
	v_lshl_add_u32 v32, v30, 12, v252
	v_readlane_b32 s14, v255, 22
	v_lshl_add_u64 v[34:35], v[32:33], 1, v[28:29]
	v_and_b32_e32 v32, 0x70, v38
	v_readlane_b32 s15, v255, 23
	v_ashrrev_i32_e32 v68, 3, v205
	s_add_i32 s11, s4, s3
	v_ashrrev_i32_e32 v94, 3, v70
	v_lshl_add_u64 v[66:67], s[14:15], 0, v[32:33]
	v_readlane_b32 s14, v255, 27
	v_add_u32_e32 v38, s11, v68
	v_mov_b32_e32 v71, 0x4000
	v_add_u32_e32 v70, s11, v94
	v_readlane_b32 s15, v255, 28
	v_lshl_add_u32 v38, v38, 6, v71
	v_mov_b32_e32 v39, v33
	v_add_u32_e32 v68, s10, v68
	v_readlane_b32 s36, v254, 43
	v_lshl_add_u32 v70, v70, 6, v71
	v_mov_b32_e32 v71, v33
	v_lshl_add_u64 v[90:91], s[14:15], 0, v[32:33]
	v_lshlrev_b64 v[38:39], 1, v[38:39]
	v_lshl_add_u32 v68, v68, 12, v252
	v_mov_b32_e32 v69, v33
	v_readlane_b32 s44, v254, 51
	v_readlane_b32 s45, v254, 52
	v_lshlrev_b64 v[92:93], 1, v[70:71]
	v_lshl_add_u64 v[42:43], v[90:91], 0, v[38:39]
	v_lshl_add_u64 v[68:69], v[68:69], 1, s[86:87]
	s_mov_b64 s[16:17], s[44:45]
	v_lshl_add_u64 v[70:71], v[66:67], 0, v[92:93]
	v_lshl_add_u64 v[90:91], v[90:91], 0, v[92:93]
	v_add_u32_e32 v92, s10, v94
	v_lshl_add_u64 v[68:69], v[68:69], 0, s[16:17]
	s_mov_b32 s7, s45
	v_lshl_add_u32 v92, v92, 12, v252
	v_mov_b32_e32 v93, v33
	v_lshl_add_u64 v[68:69], v[68:69], 0, s[6:7]
	v_lshl_add_u64 v[92:93], v[92:93], 1, s[86:87]
	v_lshl_add_u64 v[68:69], v[68:69], 0, v[32:33]
	s_movk_i32 s13, 0x1000
	v_lshl_add_u64 v[92:93], v[92:93], 0, s[16:17]
	v_add_co_u32_e32 v68, vcc, s13, v68
	v_lshl_add_u64 v[92:93], v[92:93], 0, s[6:7]
	s_nop 0
	v_addc_co_u32_e32 v69, vcc, 0, v69, vcc
	v_lshl_add_u64 v[92:93], v[92:93], 0, v[32:33]
	v_add_co_u32_e32 v94, vcc, 0x1000, v92
	v_lshl_add_u64 v[40:41], v[66:67], 0, v[38:39]
	s_nop 0
	v_addc_co_u32_e32 v95, vcc, 0, v93, vcc
	global_load_dwordx4 v[4:7], v[8:9], off
	s_nop 0
	global_load_dwordx4 v[8:11], v[8:9], off offset:2048
	s_nop 0
	global_load_dwordx4 v[12:15], v[16:17], off
	s_nop 0
	global_load_dwordx4 v[16:19], v[16:17], off offset:2048
	s_nop 0
	global_load_dwordx4 v[20:23], v[24:25], off
	s_nop 0
	global_load_dwordx4 v[24:27], v[24:25], off offset:2048
	s_nop 0
	global_load_dwordx4 v[28:31], v[34:35], off
	s_nop 0
	global_load_dwordx4 v[34:37], v[34:35], off offset:2048
	s_nop 0
	global_load_dwordx4 v[38:41], v[40:41], off
	s_nop 0
	global_load_dwordx4 v[42:45], v[42:43], off
	s_nop 0
	global_load_dwordx4 v[66:69], v[68:69], off
	s_nop 0
	global_load_dwordx4 v[70:73], v[70:71], off
	s_nop 0
	global_load_dwordx4 v[90:93], v[90:91], off
	s_nop 0
	global_load_dwordx4 v[94:97], v[94:95], off
	v_cmp_gt_i32_e32 vcc, 48, v205
	v_readlane_b32 s37, v254, 44
	v_readlane_b32 s38, v254, 45
	v_readlane_b32 s39, v254, 46
	v_readlane_b32 s40, v254, 47
	v_readlane_b32 s41, v254, 48
	v_readlane_b32 s42, v254, 49
	v_readlane_b32 s43, v254, 50
	v_readlane_b32 s46, v254, 53
	v_readlane_b32 s47, v254, 54
	v_readlane_b32 s48, v254, 55
	v_readlane_b32 s49, v254, 56
	v_readlane_b32 s50, v254, 57
	v_readlane_b32 s51, v254, 58
	s_and_saveexec_b64 s[10:11], vcc
	s_cbranch_execz .LBB0_270
	v_readlane_b32 s7, v255, 32
	v_cmp_gt_i32_e32 vcc, 32, v205
	s_nop 0
	v_mov_b32_e32 v32, s7
	v_readlane_b32 s7, v255, 36
	s_nop 1
	v_mov_b32_e32 v46, s7
	v_readlane_b32 s7, v255, 35
	v_cndmask_b32_e32 v32, v32, v46, vcc
	s_nop 0
	v_mov_b32_e32 v46, s7
	v_readlane_b32 s7, v255, 38
	s_nop 1
	v_mov_b32_e32 v47, s7
	v_cndmask_b32_e32 v46, v46, v47, vcc
	v_mov_b32_e32 v47, s81
	v_cmp_gt_i32_e32 vcc, 16, v205
	s_nop 1
	v_cndmask_b32_e32 v47, v46, v47, vcc
	v_mov_b32_e32 v46, s80
	v_cndmask_b32_e32 v46, v32, v46, vcc
	v_and_b32_e32 v32, 15, v205
	v_lshlrev_b32_e32 v32, 4, v32
	v_lshl_add_u64 v[46:47], v[46:47], 0, v[32:33]
	v_lshl_add_u64 v[46:47], v[46:47], 0, v[190:191]
	global_load_dwordx4 v[46:49], v[46:47], off offset:-512

; __device__ __forceinline__ void phase_scan(h16* Pdn, const h16* Tg, const h16* qkg, const float* gcg, const float* betag, const float* s2g, unsigned char* ldsb) {
;     ...
;                 SCAN_ST((n + 2) & 1, R2); if (n + 5 < 64) SCAN_LD(n + 5, R2);
.LBB0_271:
	s_bitcmp1_b32 s5, 0
	v_mov_b32_e32 v32, v204
	s_waitcnt lgkmcnt(0)
	s_barrier
	s_cselect_b32 s7, 0xf300, 0
	s_add_i32 s7, s7, 0
	v_lshlrev_b32_e32 v205, 4, v32
	v_and_b32_e32 v196, 0xf0, v205
	v_add_u32_e32 v196, s7, v196
	v_lshrrev_b32_e32 v197, 4, v32
	s_movk_i32 s13, 0x110
	v_add_u32_e32 v206, 0x100, v32
	v_mad_u64_u32 v[198:199], s[10:11], v197, s13, v[196:197]
	v_lshrrev_b32_e32 v197, 4, v206
	s_cmp_gt_u32 s5, 57
	s_cbranch_scc1 .Lscanld_b_full
	s_waitcnt vmcnt(28)
	s_branch .Lscanld_b_go

.Lscanld_b_go:
	ds_write_b128 v198, v[50:53]
	ds_write_b128 v198, v[54:57] offset:17408
	v_mad_u64_u32 v[198:199], s[10:11], v197, s13, v[196:197]
	v_add_u32_e32 v197, 0x200, v32
	v_lshrrev_b32_e32 v197, 4, v197
	ds_write_b128 v198, v[58:61]
	ds_write_b128 v198, v[62:65] offset:17408
	v_mad_u64_u32 v[198:199], s[10:11], v197, s13, v[196:197]
	v_add_u32_e32 v197, 0x300, v32
	v_lshrrev_b32_e32 v197, 4, v197
	v_mad_u64_u32 v[196:197], s[10:11], v197, s13, v[196:197]
	ds_write_b128 v198, v[74:77]
	ds_write_b128 v198, v[78:81] offset:17408
	ds_write_b128 v196, v[82:85]
	ds_write_b128 v196, v[86:89] offset:17408
	v_and_b32_e32 v196, 0x70, v205
	v_add_u32_e32 v196, s7, v196
	v_ashrrev_i32_e32 v197, 3, v32
	s_movk_i32 s13, 0x90
	v_mad_u64_u32 v[198:199], s[10:11], v197, s13, v[196:197]
	v_lshl_add_u32 v197, v197, 7, v196
	ds_write_b128 v198, v[98:101] offset:34816
	ds_write_b128 v198, v[102:105] offset:44032
	ds_write_b128 v197, v[126:129] offset:53248
	v_ashrrev_i32_e32 v197, 3, v206
	v_mad_u64_u32 v[198:199], s[10:11], v197, s13, v[196:197]
	v_lshl_add_u32 v196, v197, 7, v196
	v_cmp_gt_i32_e32 vcc, 48, v32
	ds_write_b128 v198, v[130:133] offset:34816
	ds_write_b128 v198, v[150:153] offset:44032
	ds_write_b128 v196, v[154:157] offset:53248
	s_and_saveexec_b64 s[10:11], vcc
	v_lshl_add_u32 v32, v32, 4, s7
	ds_write_b128 v32, v[106:109] offset:61440
	s_or_b64 exec, exec, s[10:11]
	s_cmp_gt_u32 s5, 58
	s_cbranch_scc1 .LBB0_277
	v_mov_b32_e32 v205, v204
	s_add_i32 s10, s12, s3
	v_lshlrev_b32_e32 v98, 4, v205
	v_and_b32_e32 v32, 0xf0, v98
	v_lshl_add_u64 v[82:83], s[0:1], 0, v[32:33]
	v_lshrrev_b32_e32 v32, 4, v205
	v_add_u32_e32 v32, s10, v32
	v_lshl_add_u32 v32, v32, 12, v201
	v_add_u32_e32 v130, 0x100, v205
	v_lshl_add_u64 v[54:55], v[32:33], 1, v[82:83]
	v_lshrrev_b32_e32 v32, 4, v130
	v_add_u32_e32 v32, s10, v32
	v_lshl_add_u32 v32, v32, 12, v201
	v_lshl_add_u64 v[62:63], v[32:33], 1, v[82:83]
	v_add_u32_e32 v32, 0x200, v205
	v_lshrrev_b32_e32 v32, 4, v32
	v_add_u32_e32 v32, s10, v32
	v_lshl_add_u32 v32, v32, 12, v201
	v_lshl_add_u64 v[78:79], v[32:33], 1, v[82:83]
	v_add_u32_e32 v32, 0x300, v205
	v_lshrrev_b32_e32 v32, 4, v32
	v_add_u32_e32 v32, s10, v32
	v_lshl_add_u32 v32, v32, 12, v201
	v_readlane_b32 s14, v255, 22
	v_lshl_add_u64 v[86:87], v[32:33], 1, v[82:83]
	v_and_b32_e32 v32, 0x70, v98
	v_readlane_b32 s15, v255, 23
	v_ashrrev_i32_e32 v128, 3, v205
	s_add_i32 s11, s4, s3
	v_ashrrev_i32_e32 v154, 3, v130
	v_lshl_add_u64 v[126:127], s[14:15], 0, v[32:33]
	v_readlane_b32 s14, v255, 27
	v_add_u32_e32 v98, s11, v128
	v_mov_b32_e32 v131, 0x5000
	v_add_u32_e32 v130, s11, v154
	v_readlane_b32 s15, v255, 28
	v_lshl_add_u32 v98, v98, 6, v131
	v_mov_b32_e32 v99, v33
	v_add_u32_e32 v128, s10, v128
	v_readlane_b32 s36, v254, 43
	v_lshl_add_u32 v130, v130, 6, v131
	v_mov_b32_e32 v131, v33
	v_lshl_add_u64 v[150:151], s[14:15], 0, v[32:33]
	v_lshlrev_b64 v[98:99], 1, v[98:99]
	v_lshl_add_u32 v128, v128, 12, v201
	v_mov_b32_e32 v129, v33
	v_readlane_b32 s44, v254, 51
	v_readlane_b32 s45, v254, 52
	v_lshlrev_b64 v[152:153], 1, v[130:131]
	v_lshl_add_u64 v[102:103], v[150:151], 0, v[98:99]
	v_lshl_add_u64 v[128:129], v[128:129], 1, s[86:87]
	s_mov_b64 s[16:17], s[44:45]
	v_lshl_add_u64 v[130:131], v[126:127], 0, v[152:153]
	v_lshl_add_u64 v[150:151], v[150:151], 0, v[152:153]
	v_add_u32_e32 v152, s10, v154
	v_lshl_add_u64 v[128:129], v[128:129], 0, s[16:17]
	s_mov_b32 s7, s45
	v_lshl_add_u32 v152, v152, 12, v201
	v_mov_b32_e32 v153, v33
	v_lshl_add_u64 v[128:129], v[128:129], 0, s[6:7]
	v_lshl_add_u64 v[152:153], v[152:153], 1, s[86:87]
	v_lshl_add_u64 v[128:129], v[128:129], 0, v[32:33]
	s_movk_i32 s13, 0x1000
	v_lshl_add_u64 v[152:153], v[152:153], 0, s[16:17]
	v_add_co_u32_e32 v128, vcc, s13, v128
	v_lshl_add_u64 v[152:153], v[152:153], 0, s[6:7]
	s_nop 0
	v_addc_co_u32_e32 v129, vcc, 0, v129, vcc
	v_lshl_add_u64 v[152:153], v[152:153], 0, v[32:33]
	v_add_co_u32_e32 v154, vcc, 0x1000, v152
	v_lshl_add_u64 v[100:101], v[126:127], 0, v[98:99]
	s_nop 0
	v_addc_co_u32_e32 v155, vcc, 0, v153, vcc
	global_load_dwordx4 v[50:53], v[54:55], off
	s_nop 0
	global_load_dwordx4 v[54:57], v[54:55], off offset:2048
	s_nop 0
	global_load_dwordx4 v[58:61], v[62:63], off
	s_nop 0
	global_load_dwordx4 v[62:65], v[62:63], off offset:2048
	s_nop 0
	global_load_dwordx4 v[74:77], v[78:79], off
	s_nop 0
	global_load_dwordx4 v[78:81], v[78:79], off offset:2048
	s_nop 0
	global_load_dwordx4 v[82:85], v[86:87], off
	s_nop 0
	global_load_dwordx4 v[86:89], v[86:87], off offset:2048
	s_nop 0
	global_load_dwordx4 v[98:101], v[100:101], off
	s_nop 0
	global_load_dwordx4 v[102:105], v[102:103], off
	s_nop 0
	global_load_dwordx4 v[126:129], v[128:129], off
	s_nop 0
	global_load_dwordx4 v[130:133], v[130:131], off
	s_nop 0
	global_load_dwordx4 v[150:153], v[150:151], off
	s_nop 0
	global_load_dwordx4 v[154:157], v[154:155], off
	v_cmp_gt_i32_e32 vcc, 48, v205
	v_readlane_b32 s37, v254, 44
	v_readlane_b32 s38, v254, 45
	v_readlane_b32 s39, v254, 46
	v_readlane_b32 s40, v254, 47
	v_readlane_b32 s41, v254, 48
	v_readlane_b32 s42, v254, 49
	v_readlane_b32 s43, v254, 50
	v_readlane_b32 s46, v254, 53
	v_readlane_b32 s47, v254, 54
	v_readlane_b32 s48, v254, 55
	v_readlane_b32 s49, v254, 56
	v_readlane_b32 s50, v254, 57
	v_readlane_b32 s51, v254, 58
	s_and_saveexec_b64 s[10:11], vcc
	s_cbranch_execz .LBB0_276
	v_readlane_b32 s7, v255, 32
	v_cmp_gt_i32_e32 vcc, 32, v205
	s_nop 0
	v_mov_b32_e32 v32, s7
	v_readlane_b32 s7, v255, 36
	s_nop 1
	v_mov_b32_e32 v106, s7
	v_readlane_b32 s7, v255, 35
	v_cndmask_b32_e32 v32, v32, v106, vcc
	s_nop 0
	v_mov_b32_e32 v106, s7
	v_readlane_b32 s7, v255, 38
	s_nop 1
	v_mov_b32_e32 v107, s7
	v_cndmask_b32_e32 v106, v106, v107, vcc
	v_mov_b32_e32 v107, s81
	v_cmp_gt_i32_e32 vcc, 16, v205
	s_nop 1
	v_cndmask_b32_e32 v107, v106, v107, vcc
	v_mov_b32_e32 v106, s80
	v_cndmask_b32_e32 v106, v32, v106, vcc
	v_and_b32_e32 v32, 15, v205
	v_lshlrev_b32_e32 v32, 4, v32
	v_lshl_add_u64 v[106:107], v[106:107], 0, v[32:33]
	v_lshl_add_u64 v[106:107], v[106:107], 0, v[190:191]
	global_load_dwordx4 v[106:109], v[106:107], off offset:-256

; __device__ __forceinline__ void phase_scan(h16* Pdn, const h16* Tg, const h16* qkg, const float* gcg, const float* betag, const float* s2g, unsigned char* ldsb) {
;     ...
;                 SCAN_ST((n + 3) & 1, R0); if (n + 6 < 64) SCAN_LD(n + 6, R0);
.LBB0_277:
	s_add_i32 s13, s5, 3
	s_bitcmp1_b32 s13, 0
	v_mov_b32_e32 v32, v204
	s_waitcnt lgkmcnt(0)
	s_barrier
	s_cselect_b32 s7, 0xf300, 0
	s_add_i32 s7, s7, 0
	v_lshlrev_b32_e32 v205, 4, v32
	v_and_b32_e32 v196, 0xf0, v205
	v_add_u32_e32 v196, s7, v196
	v_lshrrev_b32_e32 v197, 4, v32
	s_movk_i32 s14, 0x110
	v_add_u32_e32 v206, 0x100, v32
	v_mad_u64_u32 v[198:199], s[10:11], v197, s14, v[196:197]
	v_lshrrev_b32_e32 v197, 4, v206
	s_cmp_gt_u32 s5, 57
	s_cbranch_scc1 .Lscanld_c_full
	s_waitcnt vmcnt(28)
	s_branch .Lscanld_c_go

; #define LDS_BARRIER() do { asm volatile("s_waitcnt lgkmcnt(0)" ::: "memory"); __builtin_amdgcn_s_barrier(); asm volatile("" ::: "memory"); } while (0)
; __device__ __forceinline__ void phase_scan(h16* Pdn, const h16* Tg, const h16* qkg, const float* gcg, const float* betag, const float* s2g, unsigned char* ldsb) {
;     ...
;         if (w >= 4) {
;             h16x8 R0[15], R1[15], R2[15];
;             SCAN_LD(0, R0); SCAN_ST(0, R0);
;             SCAN_LD(1, R1); SCAN_LD(2, R2); SCAN_LD(3, R0);
;             LDS_BARRIER();
; #pragma unroll 1
;             for (int n = 0; n < 63; n += 3) {
;                 SCAN_ST((n + 1) & 1, R1); if (n + 4 < 64) SCAN_LD(n + 4, R1);
;                 LDS_BARRIER();
;                 SCAN_ST((n + 2) & 1, R2); if (n + 5 < 64) SCAN_LD(n + 5, R2);
;                 LDS_BARRIER();
;                 SCAN_ST((n + 3) & 1, R0); if (n + 6 < 64) SCAN_LD(n + 6, R0);
;                 LDS_BARRIER();
.Lscanld_c_go:
	ds_write_b128 v198, v[110:113]
	ds_write_b128 v198, v[114:117] offset:17408
	v_mad_u64_u32 v[198:199], s[10:11], v197, s14, v[196:197]
	v_add_u32_e32 v197, 0x200, v32
	v_lshrrev_b32_e32 v197, 4, v197
	ds_write_b128 v198, v[118:121]
	ds_write_b128 v198, v[122:125] offset:17408
	v_mad_u64_u32 v[198:199], s[10:11], v197, s14, v[196:197]
	v_add_u32_e32 v197, 0x300, v32
	v_lshrrev_b32_e32 v197, 4, v197
	v_mad_u64_u32 v[196:197], s[10:11], v197, s14, v[196:197]
	ds_write_b128 v198, v[134:137]
	ds_write_b128 v198, v[138:141] offset:17408
	ds_write_b128 v196, v[142:145]
	ds_write_b128 v196, v[146:149] offset:17408
	v_and_b32_e32 v196, 0x70, v205
	v_add_u32_e32 v196, s7, v196
	v_ashrrev_i32_e32 v197, 3, v32
	s_movk_i32 s14, 0x90
	v_mad_u64_u32 v[198:199], s[10:11], v197, s14, v[196:197]
	v_lshl_add_u32 v197, v197, 7, v196
	ds_write_b128 v198, v[158:161] offset:34816
	ds_write_b128 v198, v[162:165] offset:44032
	ds_write_b128 v197, v[166:169] offset:53248
	v_ashrrev_i32_e32 v197, 3, v206
	v_mad_u64_u32 v[198:199], s[10:11], v197, s14, v[196:197]
	v_lshl_add_u32 v196, v197, 7, v196
	v_cmp_gt_i32_e32 vcc, 48, v32
	ds_write_b128 v198, v[170:173] offset:34816
	ds_write_b128 v198, v[174:177] offset:44032
	ds_write_b128 v196, v[178:181] offset:53248
	s_and_saveexec_b64 s[10:11], vcc
	v_lshl_add_u32 v32, v32, 4, s7
	ds_write_b128 v32, v[0:3] offset:61440
	s_or_b64 exec, exec, s[10:11]
	s_cmp_gt_u32 s5, 57
	s_cbranch_scc1 .LBB0_264
	v_mov_b32_e32 v205, v204
	s_add_i32 s5, s12, s3
	v_lshlrev_b32_e32 v158, 4, v205
	v_and_b32_e32 v32, 0xf0, v158
	v_lshl_add_u64 v[142:143], s[0:1], 0, v[32:33]
	v_lshrrev_b32_e32 v32, 4, v205
	v_add_u32_e32 v32, s5, v32
	v_lshl_add_u32 v32, v32, 12, v200
	v_add_u32_e32 v170, 0x100, v205
	v_lshl_add_u64 v[114:115], v[32:33], 1, v[142:143]
	v_lshrrev_b32_e32 v32, 4, v170
	v_add_u32_e32 v32, s5, v32
	v_lshl_add_u32 v32, v32, 12, v200
	v_lshl_add_u64 v[122:123], v[32:33], 1, v[142:143]
	v_add_u32_e32 v32, 0x200, v205
	v_lshrrev_b32_e32 v32, 4, v32
	v_add_u32_e32 v32, s5, v32
	v_lshl_add_u32 v32, v32, 12, v200
	v_lshl_add_u64 v[138:139], v[32:33], 1, v[142:143]
	v_add_u32_e32 v32, 0x300, v205
	v_lshrrev_b32_e32 v32, 4, v32
	v_add_u32_e32 v32, s5, v32
	v_lshl_add_u32 v32, v32, 12, v200
	v_readlane_b32 s10, v255, 22
	v_lshl_add_u64 v[146:147], v[32:33], 1, v[142:143]
	v_and_b32_e32 v32, 0x70, v158
	v_readlane_b32 s11, v255, 23
	v_ashrrev_i32_e32 v168, 3, v205
	v_ashrrev_i32_e32 v178, 3, v170
	v_lshl_add_u64 v[166:167], s[10:11], 0, v[32:33]
	v_readlane_b32 s10, v255, 27
	v_readlane_b32 s11, v255, 28
	v_mov_b32_e32 v171, 0x6000
	v_mov_b32_e32 v159, v33
	v_lshl_add_u64 v[174:175], s[10:11], 0, v[32:33]
	s_add_i32 s10, s4, s3
	v_add_u32_e32 v158, s10, v168
	v_add_u32_e32 v170, s10, v178
	v_lshl_add_u32 v158, v158, 6, v171
	v_add_u32_e32 v168, s5, v168
	v_readlane_b32 s36, v254, 43
	v_lshl_add_u32 v170, v170, 6, v171
	v_mov_b32_e32 v171, v33
	v_lshlrev_b64 v[158:159], 1, v[158:159]
	v_lshl_add_u32 v168, v168, 12, v200
	v_mov_b32_e32 v169, v33
	v_readlane_b32 s44, v254, 51
	v_readlane_b32 s45, v254, 52
	v_lshlrev_b64 v[176:177], 1, v[170:171]
	v_lshl_add_u64 v[162:163], v[174:175], 0, v[158:159]
	v_lshl_add_u64 v[168:169], v[168:169], 1, s[86:87]
	s_mov_b64 s[16:17], s[44:45]
	v_lshl_add_u64 v[170:171], v[166:167], 0, v[176:177]
	v_lshl_add_u64 v[174:175], v[174:175], 0, v[176:177]
	v_add_u32_e32 v176, s5, v178
	v_lshl_add_u64 v[168:169], v[168:169], 0, s[16:17]
	s_mov_b32 s7, s45
	v_lshl_add_u32 v176, v176, 12, v200
	v_mov_b32_e32 v177, v33
	v_lshl_add_u64 v[168:169], v[168:169], 0, s[6:7]
	v_lshl_add_u64 v[176:177], v[176:177], 1, s[86:87]
	v_lshl_add_u64 v[168:169], v[168:169], 0, v[32:33]
	s_movk_i32 s11, 0x1000
	v_lshl_add_u64 v[176:177], v[176:177], 0, s[16:17]
	v_add_co_u32_e32 v168, vcc, s11, v168
	v_lshl_add_u64 v[176:177], v[176:177], 0, s[6:7]
	s_nop 0
	v_addc_co_u32_e32 v169, vcc, 0, v169, vcc
	v_lshl_add_u64 v[176:177], v[176:177], 0, v[32:33]
	v_add_co_u32_e32 v178, vcc, 0x1000, v176
	v_lshl_add_u64 v[160:161], v[166:167], 0, v[158:159]
	s_nop 0
	v_addc_co_u32_e32 v179, vcc, 0, v177, vcc
	global_load_dwordx4 v[110:113], v[114:115], off
	s_nop 0
	global_load_dwordx4 v[114:117], v[114:115], off offset:2048
	s_nop 0
	global_load_dwordx4 v[118:121], v[122:123], off
	s_nop 0
	global_load_dwordx4 v[122:125], v[122:123], off offset:2048
	s_nop 0
	global_load_dwordx4 v[134:137], v[138:139], off
	s_nop 0
	global_load_dwordx4 v[138:141], v[138:139], off offset:2048
	s_nop 0
	global_load_dwordx4 v[142:145], v[146:147], off
	s_nop 0
	global_load_dwordx4 v[146:149], v[146:147], off offset:2048
	s_nop 0
	global_load_dwordx4 v[158:161], v[160:161], off
	s_nop 0
	global_load_dwordx4 v[162:165], v[162:163], off
	s_nop 0
	global_load_dwordx4 v[166:169], v[168:169], off
	s_nop 0
	global_load_dwordx4 v[170:173], v[170:171], off
	s_nop 0
	global_load_dwordx4 v[174:177], v[174:175], off
	s_nop 0
	global_load_dwordx4 v[178:181], v[178:179], off
	v_cmp_gt_i32_e32 vcc, 48, v205
	v_readlane_b32 s37, v254, 44
	v_readlane_b32 s38, v254, 45
	v_readlane_b32 s39, v254, 46
	v_readlane_b32 s40, v254, 47
	v_readlane_b32 s41, v254, 48
	v_readlane_b32 s42, v254, 49
	v_readlane_b32 s43, v254, 50
	v_readlane_b32 s46, v254, 53
	v_readlane_b32 s47, v254, 54
	v_readlane_b32 s48, v254, 55
	v_readlane_b32 s49, v254, 56
	v_readlane_b32 s50, v254, 57
	v_readlane_b32 s51, v254, 58
	s_and_saveexec_b64 s[10:11], vcc
	s_cbranch_execz .LBB0_263
	v_readlane_b32 s5, v255, 32
	v_cmp_gt_i32_e32 vcc, 32, v205
	s_nop 0
	v_mov_b32_e32 v0, s5
	v_readlane_b32 s5, v255, 36
	s_nop 1
	v_mov_b32_e32 v1, s5
	v_readlane_b32 s5, v255, 35
	v_cndmask_b32_e32 v0, v0, v1, vcc
	s_nop 0
	v_mov_b32_e32 v1, s5
	v_readlane_b32 s5, v255, 38
	s_nop 1
	v_mov_b32_e32 v2, s5
	v_cndmask_b32_e32 v1, v1, v2, vcc
	v_mov_b32_e32 v2, s81
	v_cmp_gt_i32_e32 vcc, 16, v205
	s_nop 1
	v_cndmask_b32_e32 v1, v1, v2, vcc
	v_mov_b32_e32 v2, s80
	v_cndmask_b32_e32 v0, v0, v2, vcc
	v_and_b32_e32 v2, 15, v205
	v_lshlrev_b32_e32 v32, 4, v2
	v_lshl_add_u64 v[0:1], v[0:1], 0, v[32:33]
	v_lshl_add_u64 v[0:1], v[0:1], 0, v[190:191]
	global_load_dwordx4 v[0:3], v[0:1], off
	s_branch .LBB0_263
